# combined: ticket prefetch + ret prologue loads + diff K reads conflict-free + task-start barrier sinking
# speedup vs baseline: 1.0020x; 1.0020x over previous
; __device__ __forceinline__ float uniform_f(float x) { return __uint_as_float((unsigned)__builtin_amdgcn_readfirstlane((int)__float_as_uint(x))); }
; #define DF_COMMIT(buf) do { LAS unsigned char* bb_ = lds + (buf) * DF_BUF; \
;         _Pragma("unroll") for (int i_ = 0; i_ < 2; ++i_) { const int id_ = tid + 512 * i_, kr_ = id_ >> 5, kc_ = id_ & 31, vr_ = id_ >> 2, vc_ = id_ & 3; \
;             *(LAS u32x4*)(bb_ + kr_ * DF_KP + kc_ * 16) = kreg[i_]; *(LAS u32x4*)(bb_ + DF_KBYTES + vr_ * VP + vc_ * 16) = vreg[i_]; } } while (0)
; __device__ __forceinline__ void wg_diff_task(ParamsCP pp, int layer, LAS unsigned char* lds, int b, int h, int qb, int tid_in) {
;     ...
;     const bf16_t* PROJ = (const bf16_t*)(pp->ws + WS_BIG + BIG_PROJ); const bf16_t* VT = (const bf16_t*)(pp->ws + WS_BIG + BIG_VT);
;     const int lane = tid & 63, wave = __builtin_amdgcn_readfirstlane(tid >> 6), c16 = lane & 15, quad = lane >> 4;
;     const size_t qcol = PBUF + h * 256, kcol = PBUF + 1024 + h * 256;
;     const int vrow0 = V_DIFF + h * 256;
;     const int jraw = qb * 8 + wave; const bool active = jraw < 129; const int jq = active ? jraw : 128;
;     const int qrow0 = tile_row(b, jq);
;     const float* misc = (const float*)(pp->ws + WS_MISC) + 16 * layer;
;     const float lam = uniform_f(misc[0]), cb = uniform_f(misc[1] * LOG2E), sc = 0.08838834764831845f * LOG2E;
;     bf16x8 qf0[4], qf1[4];
;     { const bf16_t* qp = PROJ + (size_t)(qrow0 + c16) * PP + qcol + 8 * quad;
; #pragma unroll
;         for (int ks = 0; ks < 4; ++ks) { qf0[ks] = *(const bf16x8*)(qp + 32 * ks); qf1[ks] = *(const bf16x8*)(qp + 128 + 32 * ks); } }
;     f32x4 acc0[16], acc1[16];
; #pragma unroll
;     for (int e0 = 0; e0 < 16; ++e0) { acc0[e0] = (f32x4){0.f, 0.f, 0.f, 0.f}; acc1[e0] = (f32x4){0.f, 0.f, 0.f, 0.f}; }
;     float ls0 = 0.f, ls1 = 0.f;
;     u32x4 kreg[2], vreg[2];
;     ...
;     __syncthreads();
;     DF_ISSUE(0); DF_COMMIT(0);
;     __syncthreads();
.Lmx_d_noat:
	s_mov_b64 exec, s[4:5]
	v_and_b32_e32 v207, 15, v2
	v_add_u32_e32 v4, s30, v207
	s_lshl_b32 s24, s10, 8
	v_ashrrev_i32_e32 v5, 31, v4
	s_ashr_i32 s25, s24, 31
	v_lshlrev_b64 v[4:5], 12, v[4:5]
	v_bfe_u32 v208, v2, 4, 2
	v_lshl_add_u64 v[4:5], s[84:85], 0, v[4:5]
	s_lshl_b64 s[4:5], s[24:25], 1
	v_lshl_add_u64 v[4:5], v[4:5], 0, s[4:5]
	v_lshlrev_b32_e32 v0, 4, v208
	v_lshl_add_u64 v[4:5], v[4:5], 0, v[0:1]
	v_and_b32_e32 v253, 1, v208
	v_lshl_or_b32 v0, v253, 3, v0
	s_mov_b64 s[10:11], 0x8100000
	s_add_i32 s38, s24, 0x400
	v_lshl_add_u64 v[6:7], v[4:5], 0, s[10:11]
	s_mov_b32 s10, 0x8100000
	s_bitset1_b32 s9, 8
	v_add_co_u32_e32 v4, vcc, s10, v4
	s_add_u32 s4, s84, s4
	v_lshlrev_b32_e32 v10, 4, v2
	v_addc_co_u32_e32 v5, vcc, 0, v5, vcc
	s_addc_u32 s5, s85, s5
	v_and_b32_e32 v180, 0x1f0, v10
	v_mov_b32_e32 v181, v1
	global_load_dwordx4 v[114:117], v[4:5], off
	global_load_dwordx2 v[178:179], v1, s[20:21]
	global_load_dwordx4 v[118:121], v[6:7], off offset:64
	global_load_dwordx4 v[122:125], v[6:7], off offset:256
	global_load_dwordx4 v[126:129], v[6:7], off offset:320
	global_load_dwordx4 v[134:137], v[6:7], off offset:128
	global_load_dwordx4 v[138:141], v[6:7], off offset:192
	global_load_dwordx4 v[142:145], v[6:7], off offset:384
	global_load_dwordx4 v[146:149], v[6:7], off offset:448
	v_and_b32_e32 v3, 2, v2
	v_lshl_add_u64 v[4:5], s[4:5], 0, v[180:181]
	s_mov_b64 s[4:5], 0x8100800
	v_lshlrev_b32_e32 v6, 3, v2
	v_lshl_add_u64 v[182:183], v[4:5], 0, s[4:5]
	v_mov_b32_e32 v4, s9
	v_mov_b32_e32 v11, s8
	v_cmp_eq_u32_e64 s[8:9], 0, v3
	v_and_b32_e32 v181, 8, v6
	v_ashrrev_i32_e32 v209, 5, v2
	v_cndmask_b32_e64 v3, v4, v11, s[8:9]
	v_or_b32_e32 v4, v3, v181
	v_mov_b32_e32 v3, s37
	v_cmp_gt_i32_e64 s[10:11], 16, v209
	v_ashrrev_i32_e32 v12, 2, v2
	v_add_u32_e32 v2, 0x200, v2
	v_cndmask_b32_e64 v6, v3, v11, s[10:11]
	v_add_u32_e32 v6, v6, v209
	v_ashrrev_i32_e32 v7, 31, v6
	v_ashrrev_i32_e32 v5, 31, v4
	v_lshlrev_b64 v[6:7], 12, v[6:7]
	v_ashrrev_i32_e32 v210, 5, v2
	v_lshl_add_u64 v[4:5], v[4:5], 1, s[16:17]
	v_lshl_add_u64 v[6:7], v[182:183], 0, v[6:7]
	v_add_u32_e32 v13, s38, v12
	s_mov_b32 s41, 0x10200
	v_cmp_gt_i32_e64 s[12:13], 16, v210
	s_waitcnt vmcnt(63) expcnt(7) lgkmcnt(15)
	v_mad_i64_i32 v[8:9], s[4:5], v13, s41, v[4:5]
	global_load_dwordx4 v[162:165], v[6:7], off
	global_load_dwordx4 v[166:169], v[8:9], off
	v_ashrrev_i32_e32 v6, 2, v2
	v_cndmask_b32_e64 v2, v3, v11, s[12:13]
	v_add_u32_e32 v2, v2, v210
	v_ashrrev_i32_e32 v3, 31, v2
	v_lshlrev_b64 v[2:3], 12, v[2:3]
	v_lshl_add_u64 v[2:3], v[182:183], 0, v[2:3]
	v_add_u32_e32 v7, s38, v6
	global_load_dwordx4 v[170:173], v[2:3], off
	v_mad_i64_i32 v[2:3], s[4:5], v7, s41, v[4:5]
	global_load_dwordx4 v[174:177], v[2:3], off
	s_barrier
	v_mad_i64_i32 v[184:185], s[4:5], v13, s41, 0
	v_mad_i64_i32 v[186:187], s[4:5], v7, s41, 0
	v_mov_b32_e32 v2, 0x3fb8aa3b
	s_movk_i32 s5, 0x210
	v_and_b32_e32 v212, 48, v10
	v_mul_lo_u32 v213, v209, s5
	s_movk_i32 s4, 0x50
	v_add_u32_e32 v3, 0, v212
	v_mul_lo_u32 v214, v12, s4
	v_mul_lo_u32 v215, v210, s5
	v_mul_lo_u32 v216, v6, s4
	v_mov_b32_e32 v22, 0
	s_mov_b32 s38, 3
	s_mov_b32 s39, 0
	v_lshlrev_b32_e32 v211, 3, v208
	v_mul_u32_u24_e32 v217, 0x210, v207
	v_mul_u32_u24_e32 v218, 0x50, v207
	v_mov_b32_e32 v23, v22
	v_mov_b32_e32 v24, v22
	v_mov_b32_e32 v25, v22
	v_mov_b32_e32 v50, v22
	v_mov_b32_e32 v51, v22
	v_mov_b32_e32 v52, v22
	v_mov_b32_e32 v53, v22
	v_mov_b32_e32 v58, v22
	v_mov_b32_e32 v59, v22
	s_waitcnt vmcnt(11)
	v_readfirstlane_b32 s40, v179
	v_mov_b32_e32 v60, v22
	v_mov_b32_e32 v61, v22
	v_mul_f32_e32 v179, s40, v2
	v_add_u32_e32 v2, 0, v180
	v_add_u32_e32 v4, v2, v213
	v_add_u32_e32 v2, v2, v215
	s_add_i32 s40, s37, 32
	v_mov_b32_e32 v70, v22
	v_mov_b32_e32 v71, v22
	v_mov_b32_e32 v72, v22
	v_mov_b32_e32 v73, v22
	v_mov_b32_e32 v82, v22
	v_mov_b32_e32 v83, v22
	v_mov_b32_e32 v84, v22
	v_mov_b32_e32 v85, v22
	v_mov_b32_e32 v90, v22
	v_mov_b32_e32 v91, v22
	v_mov_b32_e32 v92, v22
	v_mov_b32_e32 v93, v22
	v_mov_b32_e32 v102, v22
	v_mov_b32_e32 v103, v22
	v_mov_b32_e32 v104, v22
	v_mov_b32_e32 v105, v22
	v_mov_b32_e32 v130, v22
	v_mov_b32_e32 v131, v22
	v_mov_b32_e32 v132, v22
	v_mov_b32_e32 v133, v22
	v_mov_b32_e32 v42, v22
	v_mov_b32_e32 v43, v22
	v_mov_b32_e32 v44, v22
	v_mov_b32_e32 v45, v22
	v_mov_b32_e32 v34, v22
	v_mov_b32_e32 v35, v22
	v_mov_b32_e32 v36, v22
	v_mov_b32_e32 v37, v22
	v_mov_b32_e32 v26, v22
	v_mov_b32_e32 v27, v22
	v_mov_b32_e32 v28, v22
	s_waitcnt vmcnt(3)
	ds_write_b128 v4, v[162:165]
	v_add_u32_e32 v4, v3, v214
	s_waitcnt vmcnt(2)
	ds_write_b128 v4, v[166:169] offset:16896
	v_mov_b32_e32 v29, v22
	v_mov_b32_e32 v18, v22
	v_mov_b32_e32 v19, v22
	v_mov_b32_e32 v20, v22
	v_mov_b32_e32 v21, v22
	v_mov_b32_e32 v14, v22
	s_waitcnt vmcnt(1)
	ds_write_b128 v2, v[170:173]
	v_add_u32_e32 v2, v3, v216
	v_mov_b32_e32 v15, v22
	s_waitcnt vmcnt(0)
	ds_write_b128 v2, v[174:177] offset:16896
	v_mov_b32_e32 v16, v22
	v_mov_b32_e32 v17, v22
	v_mov_b32_e32 v10, v22
	v_mov_b32_e32 v11, v22
	v_mov_b32_e32 v12, v22
	v_mov_b32_e32 v13, v22
	v_mov_b32_e32 v6, v22
	v_mov_b32_e32 v7, v22
	v_mov_b32_e32 v8, v22
	v_mov_b32_e32 v9, v22
	v_mov_b32_e32 v2, v22
	v_mov_b32_e32 v3, v22
	v_mov_b32_e32 v4, v22
	v_mov_b32_e32 v5, v22
	v_mov_b32_e32 v158, v22
	v_mov_b32_e32 v159, v22
	v_mov_b32_e32 v160, v22
	v_mov_b32_e32 v161, v22
	v_mov_b32_e32 v154, v22
	v_mov_b32_e32 v155, v22
	v_mov_b32_e32 v156, v22
	v_mov_b32_e32 v157, v22
	v_mov_b32_e32 v150, v22
	v_mov_b32_e32 v151, v22
	v_mov_b32_e32 v152, v22
	v_mov_b32_e32 v153, v22
	v_mov_b32_e32 v110, v22
	v_mov_b32_e32 v111, v22
	v_mov_b32_e32 v112, v22
	v_mov_b32_e32 v113, v22
	v_mov_b32_e32 v106, v22
	v_mov_b32_e32 v107, v22
	v_mov_b32_e32 v108, v22
	v_mov_b32_e32 v109, v22
	v_mov_b32_e32 v98, v22
	v_mov_b32_e32 v99, v22
	v_mov_b32_e32 v100, v22
	v_mov_b32_e32 v101, v22
	v_mov_b32_e32 v94, v22
	v_mov_b32_e32 v95, v22
	v_mov_b32_e32 v96, v22
	v_mov_b32_e32 v97, v22
	v_mov_b32_e32 v86, v22
	v_mov_b32_e32 v87, v22
	v_mov_b32_e32 v88, v22
	v_mov_b32_e32 v89, v22
	v_mov_b32_e32 v78, v22
	v_mov_b32_e32 v79, v22
	v_mov_b32_e32 v80, v22
	v_mov_b32_e32 v81, v22
	v_mov_b32_e32 v74, v22
	v_mov_b32_e32 v75, v22
	v_mov_b32_e32 v76, v22
	v_mov_b32_e32 v77, v22
	v_mov_b32_e32 v66, v22
	v_mov_b32_e32 v67, v22
	v_mov_b32_e32 v68, v22
	v_mov_b32_e32 v69, v22
	v_mov_b32_e32 v62, v22
	v_mov_b32_e32 v63, v22
	v_mov_b32_e32 v64, v22
	v_mov_b32_e32 v65, v22
	v_mov_b32_e32 v54, v22
	v_mov_b32_e32 v55, v22
	v_mov_b32_e32 v56, v22
	v_mov_b32_e32 v57, v22
	v_mov_b32_e32 v46, v22
	v_mov_b32_e32 v47, v22
	v_mov_b32_e32 v48, v22
	v_mov_b32_e32 v49, v22
	v_mov_b32_e32 v38, v22
	v_mov_b32_e32 v39, v22
	v_mov_b32_e32 v40, v22
	v_mov_b32_e32 v41, v22
	v_mov_b32_e32 v30, v22
	v_mov_b32_e32 v31, v22
	v_mov_b32_e32 v32, v22
	v_mov_b32_e32 v33, v22
	v_mov_b32_e32 v188, v22
	v_mov_b32_e32 v189, v22
	v_readfirstlane_b32 s4, v206
	s_nop 3
	s_bitcmp1_b32 s4, 8
	s_cbranch_scc0 .Lprio_d_skip
	s_setprio 1
